# attention main-loop block rescheduled: V fragments preloaded, PV MFMAs interleaved with exp groups, rescale skipped when alpha==1
# speedup vs baseline: 1.0056x; 1.0056x over previous
.LBB0_2407:
	s_or_b64 exec, exec, s[26:27]
	global_load_dwordx4 v[96:99], v[106:107], off
	s_add_i32 s26, s13, -1
	s_and_b32 s28, s13, 1
	v_cmp_le_i32_e32 vcc, s26, v114
	s_and_saveexec_b64 s[26:27], vcc
	s_cbranch_execz .LBB0_2409
	s_mul_i32 s29, s28, 0x5800
	s_add_i32 s29, s29, 0
	v_add3_u32 v119, s29, v116, v192
	ds_read_b128 v[32:35], v119 offset:6656
	ds_read_b128 v[36:39], v119
	ds_read_b128 v[120:123], v119 offset:32
	ds_read_b128 v[124:127], v119 offset:6688
	s_waitcnt lgkmcnt(2)
	v_mfma_f32_32x32x16_bf16 v[48:63], v[36:39], v[88:91], 0
	v_mfma_f32_32x32x16_bf16 v[32:47], v[32:35], v[88:91], 0
	s_waitcnt lgkmcnt(1)
	v_mfma_f32_32x32x16_bf16 v[48:63], v[120:123], v[84:87], v[48:63]
	s_waitcnt lgkmcnt(0)
	v_mfma_f32_32x32x16_bf16 v[32:47], v[124:127], v[84:87], v[32:47]
	ds_read_b128 v[120:123], v119 offset:64
	ds_read_b128 v[124:127], v119 offset:6720
	s_waitcnt lgkmcnt(1)
	v_mfma_f32_32x32x16_bf16 v[48:63], v[120:123], v[80:83], v[48:63]
	s_waitcnt lgkmcnt(0)
	v_mfma_f32_32x32x16_bf16 v[32:47], v[124:127], v[80:83], v[32:47]
	ds_read_b128 v[120:123], v119 offset:96
	ds_read_b128 v[124:127], v119 offset:6752
	s_waitcnt lgkmcnt(1)
	v_mfma_f32_32x32x16_bf16 v[48:63], v[120:123], v[76:79], v[48:63]
	s_waitcnt lgkmcnt(0)
	v_mfma_f32_32x32x16_bf16 v[32:47], v[124:127], v[76:79], v[32:47]
	ds_read_b128 v[120:123], v119 offset:128
	ds_read_b128 v[124:127], v119 offset:6784
	s_waitcnt lgkmcnt(1)
	v_mfma_f32_32x32x16_bf16 v[48:63], v[120:123], v[72:75], v[48:63]
	s_waitcnt lgkmcnt(0)
	v_mfma_f32_32x32x16_bf16 v[32:47], v[124:127], v[72:75], v[32:47]
	ds_read_b128 v[120:123], v119 offset:160
	ds_read_b128 v[124:127], v119 offset:6816
	s_waitcnt lgkmcnt(1)
	v_mfma_f32_32x32x16_bf16 v[48:63], v[120:123], v[68:71], v[48:63]
	s_waitcnt lgkmcnt(0)
	v_mfma_f32_32x32x16_bf16 v[32:47], v[124:127], v[68:71], v[32:47]
	v_add3_u32 v168, s29, v117, v192
	ds_read_b128 v[136:139], v168 offset:13312
	ds_read_b128 v[140:143], v168 offset:17920
	ds_read_b128 v[144:147], v168 offset:13344
	ds_read_b128 v[148:151], v168 offset:17952
	ds_read_b128 v[152:155], v168 offset:13376
	ds_read_b128 v[156:159], v168 offset:17984
	ds_read_b128 v[160:163], v168 offset:13408
	ds_read_b128 v[164:167], v168 offset:18016
	s_nop 1
	v_max_f32_e32 v119, v49, v49
	v_max_f32_e32 v120, v48, v48
	v_max_f32_e32 v119, v120, v119
	v_max3_f32 v119, v119, v50, v51
	v_max3_f32 v119, v119, v52, v53
	v_max3_f32 v119, v119, v54, v55
	v_max3_f32 v119, v119, v56, v57
	v_max3_f32 v119, v119, v58, v59
	v_max3_f32 v119, v119, v60, v61
	v_max3_f32 v119, v119, v62, v63
	v_max3_f32 v119, v119, v32, v33
	v_max3_f32 v119, v119, v34, v35
	v_max3_f32 v119, v119, v36, v37
	v_max3_f32 v119, v119, v38, v39
	v_max3_f32 v119, v119, v40, v41
	v_max3_f32 v119, v119, v42, v43
	v_max3_f32 v119, v119, v44, v45
	v_max3_f32 v119, v119, v46, v47
	v_mov_b32_e32 v120, v119
	s_nop 1
	v_permlane32_swap_b32_e32 v119, v120
	v_max3_f32 v119, v118, v119, v120
	v_sub_f32_e32 v118, v118, v119
	v_exp_f32_e32 v170, v118
	v_sub_f32_e32 v48, v48, v119
	v_exp_f32_e32 v48, v48
	v_sub_f32_e32 v49, v49, v119
	v_exp_f32_e32 v49, v49
	v_add_f32_e32 v169, 0, v48
	v_sub_f32_e32 v50, v50, v119
	v_exp_f32_e32 v50, v50
	v_add_f32_e32 v169, v49, v169
	v_sub_f32_e32 v51, v51, v119
	v_exp_f32_e32 v51, v51
	v_add_f32_e32 v169, v50, v169
	v_sub_f32_e32 v52, v52, v119
	v_exp_f32_e32 v52, v52
	v_add_f32_e32 v169, v51, v169
	v_sub_f32_e32 v53, v53, v119
	v_exp_f32_e32 v53, v53
	v_add_f32_e32 v169, v52, v169
	v_sub_f32_e32 v54, v54, v119
	v_exp_f32_e32 v54, v54
	v_add_f32_e32 v169, v53, v169
	v_sub_f32_e32 v55, v55, v119
	v_exp_f32_e32 v55, v55
	v_add_f32_e32 v169, v54, v169
	v_cvt_pk_bf16_f32 v172, v48, v49
	v_add_f32_e32 v169, v55, v169
	v_cvt_pk_bf16_f32 v173, v50, v51
	v_cvt_pk_bf16_f32 v174, v52, v53
	v_cvt_pk_bf16_f32 v175, v54, v55
	v_cmp_neq_f32_e32 vcc, 1.0, v170
	s_cbranch_vccz .Lattn_noresc
	v_pk_mul_f32 v[16:17], v[16:17], v[170:171] op_sel_hi:[1,0]
	v_pk_mul_f32 v[18:19], v[18:19], v[170:171] op_sel_hi:[1,0]
	v_pk_mul_f32 v[20:21], v[20:21], v[170:171] op_sel_hi:[1,0]
	v_pk_mul_f32 v[22:23], v[22:23], v[170:171] op_sel_hi:[1,0]
	v_pk_mul_f32 v[24:25], v[24:25], v[170:171] op_sel_hi:[1,0]
	v_pk_mul_f32 v[26:27], v[26:27], v[170:171] op_sel_hi:[1,0]
	v_pk_mul_f32 v[28:29], v[28:29], v[170:171] op_sel_hi:[1,0]
	v_pk_mul_f32 v[30:31], v[30:31], v[170:171] op_sel_hi:[1,0]
	v_pk_mul_f32 v[0:1], v[0:1], v[170:171] op_sel_hi:[1,0]
	v_pk_mul_f32 v[2:3], v[2:3], v[170:171] op_sel_hi:[1,0]
	v_pk_mul_f32 v[4:5], v[4:5], v[170:171] op_sel_hi:[1,0]
	v_pk_mul_f32 v[6:7], v[6:7], v[170:171] op_sel_hi:[1,0]
	v_pk_mul_f32 v[8:9], v[8:9], v[170:171] op_sel_hi:[1,0]
	v_pk_mul_f32 v[10:11], v[10:11], v[170:171] op_sel_hi:[1,0]
	v_pk_mul_f32 v[12:13], v[12:13], v[170:171] op_sel_hi:[1,0]
	v_pk_mul_f32 v[14:15], v[14:15], v[170:171] op_sel_hi:[1,0]
.Lattn_noresc:
	v_sub_f32_e32 v56, v56, v119
	v_exp_f32_e32 v56, v56
	s_waitcnt lgkmcnt(6)
	v_mfma_f32_32x32x16_bf16 v[16:31], v[136:139], v[172:175], v[16:31]
	v_mfma_f32_32x32x16_bf16 v[0:15], v[140:143], v[172:175], v[0:15]
	v_sub_f32_e32 v57, v57, v119
	v_exp_f32_e32 v57, v57
	v_add_f32_e32 v169, v56, v169
	v_sub_f32_e32 v58, v58, v119
	v_exp_f32_e32 v58, v58
	v_add_f32_e32 v169, v57, v169
	v_sub_f32_e32 v59, v59, v119
	v_exp_f32_e32 v59, v59
	v_add_f32_e32 v169, v58, v169
	v_sub_f32_e32 v60, v60, v119
	v_exp_f32_e32 v60, v60
	v_add_f32_e32 v169, v59, v169
	v_sub_f32_e32 v61, v61, v119
	v_exp_f32_e32 v61, v61
	v_add_f32_e32 v169, v60, v169
	v_sub_f32_e32 v62, v62, v119
	v_exp_f32_e32 v62, v62
	v_add_f32_e32 v169, v61, v169
	v_sub_f32_e32 v63, v63, v119
	v_exp_f32_e32 v63, v63
	v_add_f32_e32 v169, v62, v169
	v_cvt_pk_bf16_f32 v176, v56, v57
	v_add_f32_e32 v169, v63, v169
	v_cvt_pk_bf16_f32 v177, v58, v59
	v_cvt_pk_bf16_f32 v178, v60, v61
	v_cvt_pk_bf16_f32 v179, v62, v63
	v_sub_f32_e32 v32, v32, v119
	v_exp_f32_e32 v32, v32
	s_waitcnt lgkmcnt(4)
	v_mfma_f32_32x32x16_bf16 v[16:31], v[144:147], v[176:179], v[16:31]
	v_mfma_f32_32x32x16_bf16 v[0:15], v[148:151], v[176:179], v[0:15]
	v_sub_f32_e32 v33, v33, v119
	v_exp_f32_e32 v33, v33
	v_add_f32_e32 v169, v32, v169
	v_sub_f32_e32 v34, v34, v119
	v_exp_f32_e32 v34, v34
	v_add_f32_e32 v169, v33, v169
	v_sub_f32_e32 v35, v35, v119
	v_exp_f32_e32 v35, v35
	v_add_f32_e32 v169, v34, v169
	v_sub_f32_e32 v36, v36, v119
	v_exp_f32_e32 v36, v36
	v_add_f32_e32 v169, v35, v169
	v_sub_f32_e32 v37, v37, v119
	v_exp_f32_e32 v37, v37
	v_add_f32_e32 v169, v36, v169
	v_sub_f32_e32 v38, v38, v119
	v_exp_f32_e32 v38, v38
	v_add_f32_e32 v169, v37, v169
	v_sub_f32_e32 v39, v39, v119
	v_exp_f32_e32 v39, v39
	v_add_f32_e32 v169, v38, v169
	v_cvt_pk_bf16_f32 v180, v32, v33
	v_add_f32_e32 v169, v39, v169
	v_cvt_pk_bf16_f32 v181, v34, v35
	v_cvt_pk_bf16_f32 v182, v36, v37
	v_cvt_pk_bf16_f32 v183, v38, v39
	v_sub_f32_e32 v40, v40, v119
	v_exp_f32_e32 v40, v40
	s_waitcnt lgkmcnt(2)
	v_mfma_f32_32x32x16_bf16 v[16:31], v[152:155], v[180:183], v[16:31]
	v_mfma_f32_32x32x16_bf16 v[0:15], v[156:159], v[180:183], v[0:15]
	v_sub_f32_e32 v41, v41, v119
	v_exp_f32_e32 v41, v41
	v_add_f32_e32 v169, v40, v169
	v_sub_f32_e32 v42, v42, v119
	v_exp_f32_e32 v42, v42
	v_add_f32_e32 v169, v41, v169
	v_sub_f32_e32 v43, v43, v119
	v_exp_f32_e32 v43, v43
	v_add_f32_e32 v169, v42, v169
	v_sub_f32_e32 v44, v44, v119
	v_exp_f32_e32 v44, v44
	v_add_f32_e32 v169, v43, v169
	v_sub_f32_e32 v45, v45, v119
	v_exp_f32_e32 v45, v45
	v_add_f32_e32 v169, v44, v169
	v_sub_f32_e32 v46, v46, v119
	v_exp_f32_e32 v46, v46
	v_add_f32_e32 v169, v45, v169
	v_sub_f32_e32 v47, v47, v119
	v_exp_f32_e32 v47, v47
	v_add_f32_e32 v169, v46, v169
	v_cvt_pk_bf16_f32 v184, v40, v41
	v_add_f32_e32 v169, v47, v169
	v_cvt_pk_bf16_f32 v185, v42, v43
	v_cvt_pk_bf16_f32 v186, v44, v45
	v_cvt_pk_bf16_f32 v187, v46, v47
	v_fmac_f32_e32 v169, v115, v170
	v_mov_b32_e32 v118, v119
	v_mov_b32_e32 v115, v169
	s_waitcnt lgkmcnt(0)
	v_mfma_f32_32x32x16_bf16 v[16:31], v[160:163], v[184:187], v[16:31]
	v_mfma_f32_32x32x16_bf16 v[0:15], v[164:167], v[184:187], v[0:15]
